# v10 + mlstm_combine row loop software-pipelined (head_norm loads hoisted, next row prefetched into landing regs)
# speedup vs baseline: 1.0016x; 1.0016x over previous
; DI unsigned pk2(float lo, float hi) { f32x2 v = {lo, hi}; bf16x2_t b = __builtin_convertvector(v, bf16x2_t); return __builtin_bit_cast(unsigned, b); }
; DI float bflo(unsigned u) { return __uint_as_float(u << 16); }
; DI float bfhi(unsigned u) { return __uint_as_float(u & 0xffff0000u); }
; DI void mlstm_combine_phase(bf16_t* Hfw, const bf16_t* Hbw, const bf16_t* proj, const float* hn, int G, int bid) {
;     int tid_ = threadIdx.x; asm volatile("" : "+v"(tid_)); asm volatile("" : "+s"(bid)); const int tid = tid_, wid = tid >> 6, lane = tid & 63;
;     const int gw = bid * 8 + wid, NGW = G * 8;
;     for (int row = gw; row < T; row += NGW) {
;         u32x4 f[2], b[2], o[2];
; #pragma unroll
;         for (int q = 0; q < 2; ++q) {
;             f[q] = __builtin_nontemporal_load((const u32x4*)(Hfw + (size_t)row * D + q * 512 + 8 * lane));
;             b[q] = __builtin_nontemporal_load((const u32x4*)(Hbw + (size_t)row * D + q * 512 + 8 * lane));
;             o[q] = __builtin_nontemporal_load((const u32x4*)(proj + (size_t)row * NPROJ + 2048 + q * 512 + 8 * lane));
;         }
; #pragma unroll
;         for (int q = 0; q < 2; ++q) {
;             float hs[8], ov[8]; float ss = 0.f;
; #pragma unroll
;             for (int i = 0; i < 4; ++i) {
;                 hs[2 * i] = bflo(f[q][i]) + bflo(b[q][i]); hs[2 * i + 1] = bfhi(f[q][i]) + bfhi(b[q][i]);
;                 ov[2 * i] = bflo(o[q][i]); ov[2 * i + 1] = bfhi(o[q][i]);
;             }
; #pragma unroll
;             for (int i = 0; i < 8; ++i) ss += hs[i] * hs[i];
;             ss += __shfl_xor(ss, 1); ss += __shfl_xor(ss, 2); ss += __shfl_xor(ss, 4); ss += __shfl_xor(ss, 8); ss += __shfl_xor(ss, 16);
;             const float rstd = rsqrtf(ss * (1.0f / 256.0f) + RMS_EPS);
;             const float* hp = hn + q * 512 + 8 * lane;
;             u32x4 w;
; #pragma unroll
;             for (int i = 0; i < 4; ++i) {
;                 const float y0 = hs[2 * i] * rstd * hp[2 * i] / (1.0f + __expf(-ov[2 * i]));
;                 const float y1 = hs[2 * i + 1] * rstd * hp[2 * i + 1] / (1.0f + __expf(-ov[2 * i + 1]));
;                 w[i] = pk2(y0, y1);
;             }
;             *(u32x4*)(Hfw + (size_t)row * D + q * 512 + 8 * lane) = w;
;         }
;     }
; }
.LBB0_930:
	s_or_b64 exec, exec, s[0:1]
	v_mov_b32_e32 v1, v253
	s_mov_b32 s0, s92
	s_waitcnt lgkmcnt(0)
	s_barrier
	s_lshl_b32 s2, s0, 3
	v_ashrrev_i32_e32 v0, 6, v1
	s_waitcnt vmcnt(8)
	v_add_u32_e32 v17, s2, v0
	s_mov_b32 s0, 0x18000
	v_cmp_gt_i32_e32 vcc, s0, v17
	s_and_saveexec_b64 s[0:1], vcc
	s_cbranch_execz .LBB0_933
	v_mbcnt_hi_u32_b32 v2, -1, v238
	v_and_b32_e32 v4, 64, v2
	v_xor_b32_e32 v3, 1, v2
	v_add_u32_e32 v4, 64, v4
	v_cmp_lt_i32_e32 vcc, v3, v4
	v_readlane_b32 s4, v254, 38
	v_mov_b32_e32 v9, 0
	v_cndmask_b32_e32 v3, v2, v3, vcc
	s_waitcnt vmcnt(6)
	v_lshlrev_b32_e32 v24, 2, v3
	v_xor_b32_e32 v3, 2, v2
	v_cmp_lt_i32_e32 vcc, v3, v4
	v_readlane_b32 s6, v254, 40
	v_readlane_b32 s7, v254, 41
	v_cndmask_b32_e32 v3, v2, v3, vcc
	v_lshlrev_b32_e32 v25, 2, v3
	v_xor_b32_e32 v3, 4, v2
	v_cmp_lt_i32_e32 vcc, v3, v4
	s_ashr_i32 s3, s2, 31
	s_movk_i32 s4, 0x1800
	v_cndmask_b32_e32 v3, v2, v3, vcc
	v_lshlrev_b32_e32 v26, 2, v3
	v_xor_b32_e32 v3, 8, v2
	v_cmp_lt_i32_e32 vcc, v3, v4
	v_readlane_b32 s18, v254, 52
	v_readlane_b32 s19, v254, 53
	v_cndmask_b32_e32 v3, v2, v3, vcc
	v_lshlrev_b32_e32 v27, 2, v3
	v_xor_b32_e32 v3, 16, v2
	v_cmp_lt_i32_e32 vcc, v3, v4
	s_ashr_i32 s41, s40, 31
	s_lshl_b64 s[18:19], s[40:41], 11
	v_cndmask_b32_e32 v2, v2, v3, vcc
	s_waitcnt vmcnt(5)
	v_lshlrev_b32_e32 v28, 2, v2
	v_lshlrev_b32_e32 v2, 5, v1
	v_and_b32_e32 v8, 0x7e0, v2
	v_and_b32_e32 v1, 63, v1
	v_lshl_add_u64 v[10:11], s[6:7], 0, v[8:9]
	v_lshlrev_b32_e32 v8, 4, v1
	v_ashrrev_i32_e32 v1, 31, v0
	v_lshl_add_u64 v[0:1], v[0:1], 0, s[2:3]
	v_mov_b64_e32 v[2:3], s[68:69]
	v_mad_u64_u32 v[12:13], s[2:3], v0, s4, v[2:3]
	v_mad_i32_i24 v13, v1, s4, v13
	v_lshlrev_b64 v[0:1], 11, v[0:1]
	s_mul_hi_i32 s3, s40, 0x1800
	s_mul_i32 s2, s40, 0x1800
	v_lshl_add_u64 v[14:15], s[68:69], 0, v[0:1]
	s_mov_b64 s[20:21], 0
	s_mov_b32 s22, 0x3b800000
	v_mov_b32_e32 v16, 0x358637bd
	s_mov_b32 s23, 0x800000
	s_mov_b32 s24, 0x17fff
	v_readlane_b32 s5, v254, 39
	v_readlane_b32 s8, v254, 42
	v_readlane_b32 s9, v254, 43
	v_readlane_b32 s10, v254, 44
	v_readlane_b32 s11, v254, 45
	v_readlane_b32 s12, v254, 46
	v_readlane_b32 s13, v254, 47
	v_readlane_b32 s14, v254, 48
	v_readlane_b32 s15, v254, 49
	v_readlane_b32 s16, v254, 50
	v_readlane_b32 s17, v254, 51
	global_load_dwordx4 v[100:103], v[10:11], off offset:16
	global_load_dwordx4 v[104:107], v[10:11], off
	global_load_dwordx4 v[108:111], v[10:11], off offset:2048
	global_load_dwordx4 v[112:115], v[10:11], off offset:2064
	v_lshl_add_u64 v[142:143], v[14:15], 0, v[8:9]
	v_lshl_add_u64 v[144:145], v[12:13], 0, v[8:9]
	s_nop 0
	v_add_co_u32_e32 v22, vcc, 0x3a00000, v142
	s_nop 1
	v_addc_co_u32_e32 v23, vcc, 0, v143, vcc
	v_add_co_u32_e32 v142, vcc, 0x33a00000, v142
	s_nop 1
	v_addc_co_u32_e32 v143, vcc, 0, v143, vcc
	v_add_co_u32_e32 v144, vcc, 0xfa01000, v144
	s_nop 1
	v_addc_co_u32_e32 v145, vcc, 0, v145, vcc
	global_load_dwordx4 v[116:119], v[22:23], off nt
	global_load_dwordx4 v[120:123], v[22:23], off offset:1024 nt
	global_load_dwordx4 v[124:127], v[142:143], off nt
	global_load_dwordx4 v[128:131], v[142:143], off offset:1024 nt
	global_load_dwordx4 v[132:135], v[144:145], off nt
	global_load_dwordx4 v[136:139], v[144:145], off offset:1024 nt
	v_lshl_add_u64 v[12:13], v[12:13], 0, s[2:3]
	v_lshl_add_u64 v[14:15], v[14:15], 0, s[18:19]
.LBB0_932:
	s_waitcnt vmcnt(0)
	v_lshlrev_b32_e32 v50, 16, v119
	v_and_b32_e32 v51, 0xffff0000, v119
	v_lshlrev_b32_e32 v52, 16, v118
	v_and_b32_e32 v53, 0xffff0000, v118
	v_lshlrev_b32_e32 v32, 16, v117
	v_and_b32_e32 v33, 0xffff0000, v117
	v_lshlrev_b32_e32 v54, 16, v116
	v_and_b32_e32 v55, 0xffff0000, v116
	v_lshlrev_b32_e32 v30, 16, v123
	v_and_b32_e32 v31, 0xffff0000, v123
	v_lshlrev_b32_e32 v56, 16, v122
	v_and_b32_e32 v57, 0xffff0000, v122
	v_lshlrev_b32_e32 v36, 16, v121
	v_and_b32_e32 v37, 0xffff0000, v121
	v_lshlrev_b32_e32 v58, 16, v120
	v_and_b32_e32 v59, 0xffff0000, v120
	v_lshlrev_b32_e32 v34, 16, v127
	v_and_b32_e32 v35, 0xffff0000, v127
	v_lshlrev_b32_e32 v60, 16, v126
	v_and_b32_e32 v61, 0xffff0000, v126
	v_lshlrev_b32_e32 v40, 16, v125
	v_and_b32_e32 v41, 0xffff0000, v125
	v_lshlrev_b32_e32 v62, 16, v124
	v_and_b32_e32 v63, 0xffff0000, v124
	v_lshlrev_b32_e32 v66, 16, v128
	v_and_b32_e32 v67, 0xffff0000, v128
	v_lshlrev_b32_e32 v38, 16, v131
	v_and_b32_e32 v39, 0xffff0000, v131
	v_lshlrev_b32_e32 v64, 16, v130
	v_and_b32_e32 v65, 0xffff0000, v130
	v_lshlrev_b32_e32 v44, 16, v129
	v_and_b32_e32 v45, 0xffff0000, v129
	v_lshlrev_b32_e32 v29, 16, v132
	v_and_b32_e32 v42, 0xffff0000, v132
	v_lshlrev_b32_e32 v43, 16, v133
	v_and_b32_e32 v68, 0xffff0000, v133
	v_pk_add_f32 v[18:19], v[50:51], v[34:35]
	v_pk_add_f32 v[32:33], v[32:33], v[40:41]
	v_pk_add_f32 v[34:35], v[54:55], v[62:63]
	v_pk_add_f32 v[40:41], v[58:59], v[66:67]
	v_lshlrev_b32_e32 v69, 16, v134
	v_and_b32_e32 v70, 0xffff0000, v134
	v_lshlrev_b32_e32 v71, 16, v135
	v_and_b32_e32 v72, 0xffff0000, v135
	v_pk_add_f32 v[20:21], v[52:53], v[60:61]
	v_lshlrev_b32_e32 v50, 16, v136
	v_and_b32_e32 v51, 0xffff0000, v136
	v_lshlrev_b32_e32 v52, 16, v137
	v_and_b32_e32 v53, 0xffff0000, v137
	v_lshlrev_b32_e32 v54, 16, v138
	v_and_b32_e32 v48, 0xffff0000, v138
	v_lshlrev_b32_e32 v55, 16, v139
	v_and_b32_e32 v49, 0xffff0000, v139
	v_add_u32_e32 v17, s40, v17
	v_cmp_lt_i32_e64 s[4:5], s24, v17
	s_or_b64 s[20:21], s[4:5], s[20:21]
	s_and_b64 vcc, exec, s[4:5]
	s_cbranch_vccnz .Lmc_skip_pf
	v_lshl_add_u64 v[142:143], v[14:15], 0, v[8:9]
	v_lshl_add_u64 v[144:145], v[12:13], 0, v[8:9]
	s_nop 0
	v_add_co_u32_e32 v140, vcc, 0x3a00000, v142
	s_nop 1
	v_addc_co_u32_e32 v141, vcc, 0, v143, vcc
	v_add_co_u32_e32 v142, vcc, 0x33a00000, v142
	s_nop 1
	v_addc_co_u32_e32 v143, vcc, 0, v143, vcc
	v_add_co_u32_e32 v144, vcc, 0xfa01000, v144
	s_nop 1
	v_addc_co_u32_e32 v145, vcc, 0, v145, vcc
	global_load_dwordx4 v[116:119], v[140:141], off nt
	global_load_dwordx4 v[120:123], v[140:141], off offset:1024 nt
	global_load_dwordx4 v[124:127], v[142:143], off nt
	global_load_dwordx4 v[128:131], v[142:143], off offset:1024 nt
	global_load_dwordx4 v[132:135], v[144:145], off nt
	global_load_dwordx4 v[136:139], v[144:145], off offset:1024 nt
	v_lshl_add_u64 v[12:13], v[12:13], 0, s[2:3]
	v_lshl_add_u64 v[14:15], v[14:15], 0, s[18:19]
; DI unsigned pk2(float lo, float hi) { f32x2 v = {lo, hi}; bf16x2_t b = __builtin_convertvector(v, bf16x2_t); return __builtin_bit_cast(unsigned, b); }
; DI float bflo(unsigned u) { return __uint_as_float(u << 16); }
; DI float bfhi(unsigned u) { return __uint_as_float(u & 0xffff0000u); }
; DI void mlstm_combine_phase(bf16_t* Hfw, const bf16_t* Hbw, const bf16_t* proj, const float* hn, int G, int bid) {
;     ...
;         for (int q = 0; q < 2; ++q) {
;             float hs[8], ov[8]; float ss = 0.f;
; #pragma unroll
;             for (int i = 0; i < 4; ++i) {
;                 hs[2 * i] = bflo(f[q][i]) + bflo(b[q][i]); hs[2 * i + 1] = bfhi(f[q][i]) + bfhi(b[q][i]);
;                 ov[2 * i] = bflo(o[q][i]); ov[2 * i + 1] = bfhi(o[q][i]);
;             }
; #pragma unroll
;             for (int i = 0; i < 8; ++i) ss += hs[i] * hs[i];
;             ss += __shfl_xor(ss, 1); ss += __shfl_xor(ss, 2); ss += __shfl_xor(ss, 4); ss += __shfl_xor(ss, 8); ss += __shfl_xor(ss, 16);
;             const float rstd = rsqrtf(ss * (1.0f / 256.0f) + RMS_EPS);
;             const float* hp = hn + q * 512 + 8 * lane;
;             u32x4 w;
; #pragma unroll
;             for (int i = 0; i < 4; ++i) {
;                 const float y0 = hs[2 * i] * rstd * hp[2 * i] / (1.0f + __expf(-ov[2 * i]));
;                 const float y1 = hs[2 * i + 1] * rstd * hp[2 * i + 1] / (1.0f + __expf(-ov[2 * i + 1]));
;                 w[i] = pk2(y0, y1);
.Lmc_skip_pf:
	v_pk_add_f32 v[30:31], v[30:31], v[38:39]
	v_pk_add_f32 v[38:39], v[56:57], v[64:65]
	v_pk_add_f32 v[36:37], v[36:37], v[44:45]
	v_mov_b32_e32 v56, v41
	v_mov_b32_e32 v57, v35
	v_mul_f32_e32 v59, 0xbfb8aa3b, v42
	v_mul_f32_e32 v60, 0xbfb8aa3b, v43
	v_mul_f32_e32 v61, 0xbfb8aa3b, v68
	v_mul_f32_e32 v62, 0xbfb8aa3b, v69
	v_mul_f32_e32 v63, 0xbfb8aa3b, v70
	v_mul_f32_e32 v64, 0xbfb8aa3b, v71
	v_mul_f32_e32 v65, 0xbfb8aa3b, v72
	v_pk_mul_f32 v[42:43], v[18:19], v[18:19]
	v_pk_mul_f32 v[44:45], v[20:21], v[20:21]
	v_pk_mul_f32 v[46:47], v[32:33], v[32:33]
	v_mul_f32_e32 v66, 0xbfb8aa3b, v50
	v_mul_f32_e32 v67, 0xbfb8aa3b, v51
	v_mul_f32_e32 v68, 0xbfb8aa3b, v52
	v_mul_f32_e32 v69, 0xbfb8aa3b, v53
	v_mul_f32_e32 v70, 0xbfb8aa3b, v54
	v_mul_f32_e32 v71, 0xbfb8aa3b, v48
	v_mul_f32_e32 v72, 0xbfb8aa3b, v55
	v_mul_f32_e32 v73, 0xbfb8aa3b, v49
	v_pk_mul_f32 v[48:49], v[30:31], v[30:31]
	v_pk_mul_f32 v[50:51], v[38:39], v[38:39]
	v_pk_mul_f32 v[52:53], v[36:37], v[36:37]
	v_mov_b32_e32 v54, v40
	v_mov_b32_e32 v55, v34
	v_pk_mul_f32 v[56:57], v[56:57], v[56:57]
	v_mov_b32_e32 v74, v52
	v_mov_b32_e32 v75, v46
	v_mov_b32_e32 v46, v53
	v_mov_b32_e32 v52, v50
	v_mov_b32_e32 v53, v44
	v_mov_b32_e32 v44, v51
	v_mov_b32_e32 v50, v48
	v_mov_b32_e32 v51, v42
	v_mov_b32_e32 v42, v49
	v_pk_fma_f32 v[48:49], v[54:55], v[54:55], v[56:57]
	v_mul_f32_e32 v29, 0xbfb8aa3b, v29
	v_pk_add_f32 v[48:49], v[74:75], v[48:49]
	v_exp_f32_e32 v58, v29
	v_pk_add_f32 v[46:47], v[46:47], v[48:49]
	v_exp_f32_e32 v59, v59
	v_pk_add_f32 v[46:47], v[52:53], v[46:47]
	v_exp_f32_e32 v60, v60
	v_pk_add_f32 v[44:45], v[44:45], v[46:47]
	v_exp_f32_e32 v61, v61
	v_pk_add_f32 v[44:45], v[50:51], v[44:45]
	v_exp_f32_e32 v64, v64
	v_pk_add_f32 v[42:43], v[42:43], v[44:45]
	ds_bpermute_b32 v45, v24, v43
	ds_bpermute_b32 v44, v24, v42
	v_exp_f32_e32 v65, v65
	v_exp_f32_e32 v66, v66
	v_exp_f32_e32 v67, v67
	v_exp_f32_e32 v62, v62
	s_waitcnt lgkmcnt(0)
	v_pk_add_f32 v[42:43], v[42:43], v[44:45]
	ds_bpermute_b32 v45, v25, v43
	ds_bpermute_b32 v44, v25, v42
	v_exp_f32_e32 v63, v63
	v_pk_add_f32 v[56:57], v[58:59], 1.0 op_sel_hi:[1,0]
	v_exp_f32_e32 v68, v68
	v_exp_f32_e32 v69, v69
	s_waitcnt lgkmcnt(0)
	v_pk_add_f32 v[42:43], v[42:43], v[44:45]
	ds_bpermute_b32 v45, v26, v43
	ds_bpermute_b32 v44, v26, v42
	v_exp_f32_e32 v72, v72
	v_exp_f32_e32 v73, v73
	v_pk_add_f32 v[54:55], v[60:61], 1.0 op_sel_hi:[1,0]
	v_exp_f32_e32 v70, v70
	s_waitcnt lgkmcnt(0)
	v_pk_add_f32 v[42:43], v[42:43], v[44:45]
	ds_bpermute_b32 v45, v27, v43
	ds_bpermute_b32 v44, v27, v42
	v_exp_f32_e32 v71, v71
	v_pk_add_f32 v[58:59], v[64:65], 1.0 op_sel_hi:[1,0]
	v_pk_add_f32 v[64:65], v[66:67], 1.0 op_sel_hi:[1,0]
	v_pk_add_f32 v[48:49], v[62:63], 1.0 op_sel_hi:[1,0]
	s_waitcnt lgkmcnt(0)
	v_pk_add_f32 v[42:43], v[42:43], v[44:45]
	ds_bpermute_b32 v45, v28, v43
	ds_bpermute_b32 v44, v28, v42
	v_pk_add_f32 v[62:63], v[68:69], 1.0 op_sel_hi:[1,0]
	v_pk_add_f32 v[52:53], v[72:73], 1.0 op_sel_hi:[1,0]
	v_pk_add_f32 v[60:61], v[70:71], 1.0 op_sel_hi:[1,0]
	s_waitcnt lgkmcnt(0)
	v_pk_add_f32 v[42:43], v[42:43], v[44:45]
	s_nop 0
	v_pk_fma_f32 v[42:43], v[42:43], s[22:23], v[16:17] op_sel_hi:[1,0,0]
	s_nop 0
	v_mul_f32_e32 v29, 0x4b800000, v43
	v_cmp_gt_f32_e64 s[4:5], s23, v43
	v_mul_f32_e32 v44, 0x4b800000, v42
	v_cmp_gt_f32_e32 vcc, s23, v42
	v_cndmask_b32_e64 v29, v43, v29, s[4:5]
	v_rsq_f32_e32 v29, v29
	v_cndmask_b32_e32 v42, v42, v44, vcc
	v_rsq_f32_e32 v43, v42
	v_mul_f32_e32 v42, 0x45800000, v29
	v_cndmask_b32_e64 v42, v29, v42, s[4:5]
	v_pk_mul_f32 v[34:35], v[34:35], v[42:43] op_sel_hi:[1,0]
	v_pk_mul_f32 v[20:21], v[20:21], v[42:43] op_sel_hi:[1,0]
	v_pk_mul_f32 v[4:5], v[104:105], v[34:35]
	v_pk_mul_f32 v[32:33], v[32:33], v[42:43] op_sel_hi:[1,0]
	v_pk_mul_f32 v[18:19], v[18:19], v[42:43] op_sel_hi:[1,0]
	v_pk_mul_f32 v[20:21], v[100:101], v[20:21]
	v_div_scale_f32 v0, s[4:5], v57, v57, v5
	v_pk_mul_f32 v[6:7], v[106:107], v[32:33]
	v_pk_mul_f32 v[18:19], v[102:103], v[18:19]
	v_div_scale_f32 v2, s[4:5], v56, v56, v4
	v_rcp_f32_e32 v51, v0
	v_div_scale_f32 v29, s[6:7], v55, v55, v7
	v_rcp_f32_e32 v66, v2
	v_div_scale_f32 v33, s[8:9], v54, v54, v6
	v_rcp_f32_e32 v67, v29
	v_mul_f32_e32 v44, 0x45800000, v43
	v_div_scale_f32 v35, s[10:11], v49, v49, v21
	v_rcp_f32_e32 v68, v33
	v_cndmask_b32_e32 v44, v43, v44, vcc
	v_div_scale_f32 v43, s[12:13], v48, v48, v20
	v_rcp_f32_e32 v69, v35
	v_fma_f32 v73, -v0, v51, 1.0
	v_pk_mul_f32 v[40:41], v[40:41], v[44:45] op_sel_hi:[1,0]
	v_pk_mul_f32 v[36:37], v[36:37], v[44:45] op_sel_hi:[1,0]
	v_pk_mul_f32 v[38:39], v[38:39], v[44:45] op_sel_hi:[1,0]
	v_pk_mul_f32 v[30:31], v[30:31], v[44:45] op_sel_hi:[1,0]
	v_div_scale_f32 v1, vcc, v5, v57, v5
	v_div_scale_f32 v45, s[14:15], v59, v59, v19
	v_rcp_f32_e32 v70, v43
	v_fma_f32 v74, -v2, v66, 1.0
	v_fmac_f32_e32 v51, v73, v51
	v_div_scale_f32 v3, s[4:5], v4, v56, v4
	v_div_scale_f32 v47, s[16:17], v58, v58, v18
	v_rcp_f32_e32 v71, v45
	v_fma_f32 v75, -v29, v67, 1.0
	v_fmac_f32_e32 v66, v74, v66
	v_mul_f32_e32 v73, v1, v51
	v_div_scale_f32 v32, s[6:7], v7, v55, v7
	v_rcp_f32_e32 v72, v47
	v_fma_f32 v76, -v33, v68, 1.0
	v_fmac_f32_e32 v67, v75, v67
	v_mul_f32_e32 v74, v3, v66
	v_fma_f32 v81, -v0, v73, v1
	v_div_scale_f32 v34, s[8:9], v6, v54, v6
	v_fma_f32 v77, -v35, v69, 1.0
	v_fmac_f32_e32 v68, v76, v68
	v_mul_f32_e32 v75, v32, v67
	v_fma_f32 v82, -v2, v74, v3
	v_fmac_f32_e32 v73, v81, v51
	v_div_scale_f32 v42, s[10:11], v21, v49, v21
	v_fma_f32 v78, -v43, v70, 1.0
; DI unsigned pk2(float lo, float hi) { f32x2 v = {lo, hi}; bf16x2_t b = __builtin_convertvector(v, bf16x2_t); return __builtin_bit_cast(unsigned, b); }
; DI void mlstm_combine_phase(bf16_t* Hfw, const bf16_t* Hbw, const bf16_t* proj, const float* hn, int G, int bid) {
;     ...
;             const float rstd = rsqrtf(ss * (1.0f / 256.0f) + RMS_EPS);
;             const float* hp = hn + q * 512 + 8 * lane;
;             u32x4 w;
; #pragma unroll
;             for (int i = 0; i < 4; ++i) {
;                 const float y0 = hs[2 * i] * rstd * hp[2 * i] / (1.0f + __expf(-ov[2 * i]));
;                 const float y1 = hs[2 * i + 1] * rstd * hp[2 * i + 1] / (1.0f + __expf(-ov[2 * i + 1]));
;                 w[i] = pk2(y0, y1);
;             }
;             *(u32x4*)(Hfw + (size_t)row * D + q * 512 + 8 * lane) = w;
	v_fmac_f32_e32 v69, v77, v69
	v_mul_f32_e32 v76, v34, v68
	v_fma_f32 v83, -v29, v75, v32
	v_fmac_f32_e32 v74, v82, v66
	v_fma_f32 v0, -v0, v73, v1
	v_div_scale_f32 v44, s[12:13], v20, v48, v20
	v_fma_f32 v79, -v45, v71, 1.0
	v_fmac_f32_e32 v70, v78, v70
	v_mul_f32_e32 v77, v42, v69
	v_fma_f32 v84, -v33, v76, v34
	v_fmac_f32_e32 v75, v83, v67
	v_fma_f32 v1, -v2, v74, v3
	v_div_fmas_f32 v0, v0, v51, v73
	s_mov_b64 vcc, s[4:5]
	v_div_scale_f32 v46, s[14:15], v19, v59, v19
	v_fma_f32 v80, -v47, v72, 1.0
	v_fmac_f32_e32 v71, v79, v71
	v_mul_f32_e32 v78, v44, v70
	v_fma_f32 v85, -v35, v77, v42
	v_fmac_f32_e32 v76, v84, v68
	v_fma_f32 v2, -v29, v75, v32
	v_div_fmas_f32 v1, v1, v66, v74
	s_mov_b64 vcc, s[6:7]
	v_div_scale_f32 v50, s[16:17], v18, v58, v18
	v_fmac_f32_e32 v72, v80, v72
	v_mul_f32_e32 v79, v46, v71
	v_fma_f32 v86, -v43, v78, v44
	v_fmac_f32_e32 v77, v85, v69
	v_fma_f32 v3, -v33, v76, v34
	v_div_fixup_f32 v0, v0, v57, v5
	v_div_fixup_f32 v1, v1, v56, v4
	v_div_fmas_f32 v2, v2, v67, v75
	s_mov_b64 vcc, s[8:9]
	v_mul_f32_e32 v80, v50, v72
	v_fma_f32 v87, -v45, v79, v46
	v_fmac_f32_e32 v78, v86, v70
	v_fma_f32 v29, -v35, v77, v42
	v_cvt_pk_bf16_f32 v0, v1, v0
	v_div_fixup_f32 v1, v2, v55, v7
	v_div_fmas_f32 v2, v3, v68, v76
	s_mov_b64 vcc, s[10:11]
	v_fma_f32 v88, -v47, v80, v50
	v_fmac_f32_e32 v79, v87, v71
	v_fma_f32 v32, -v43, v78, v44
	v_div_fixup_f32 v2, v2, v54, v6
	v_div_fmas_f32 v3, v29, v69, v77
	s_mov_b64 vcc, s[12:13]
	v_fmac_f32_e32 v80, v88, v72
	v_fma_f32 v33, -v45, v79, v46
	v_cvt_pk_bf16_f32 v1, v2, v1
	v_div_fixup_f32 v2, v3, v49, v21
	v_div_fmas_f32 v3, v32, v70, v78
	s_mov_b64 vcc, s[14:15]
	v_fma_f32 v34, -v47, v80, v50
	v_div_fixup_f32 v3, v3, v48, v20
	v_div_fmas_f32 v4, v33, v71, v79
	s_mov_b64 vcc, s[16:17]
	v_cvt_pk_bf16_f32 v2, v3, v2
	v_div_fixup_f32 v3, v4, v59, v19
	v_div_fmas_f32 v4, v34, v72, v80
	v_div_fixup_f32 v4, v4, v58, v18
	v_cvt_pk_bf16_f32 v3, v4, v3
	global_store_dwordx4 v[22:23], v[0:3], off
	s_nop 1
	v_pk_mul_f32 v[0:1], v[108:109], v[40:41]
	s_nop 0
	v_div_scale_f32 v18, s[4:5], v65, v65, v1
	v_pk_mul_f32 v[2:3], v[110:111], v[36:37]
	v_div_scale_f32 v20, s[4:5], v64, v64, v0
	v_rcp_f32_e32 v41, v18
	v_div_scale_f32 v29, s[6:7], v63, v63, v3
	v_rcp_f32_e32 v42, v20
	v_pk_mul_f32 v[4:5], v[112:113], v[38:39]
	v_pk_mul_f32 v[6:7], v[114:115], v[30:31]
	v_div_scale_f32 v31, s[8:9], v62, v62, v2
	v_rcp_f32_e32 v43, v29
	v_div_scale_f32 v33, s[10:11], v61, v61, v5
	v_rcp_f32_e32 v44, v31
	v_div_scale_f32 v35, s[12:13], v60, v60, v4
	v_rcp_f32_e32 v45, v33
	v_fma_f32 v49, -v18, v41, 1.0
	v_div_scale_f32 v19, vcc, v1, v65, v1
	v_div_scale_f32 v37, s[14:15], v53, v53, v7
	v_rcp_f32_e32 v46, v35
	v_fma_f32 v50, -v20, v42, 1.0
	v_fmac_f32_e32 v41, v49, v41
	v_div_scale_f32 v21, s[4:5], v0, v64, v0
	v_div_scale_f32 v39, s[16:17], v52, v52, v6
	v_rcp_f32_e32 v47, v37
	v_fma_f32 v51, -v29, v43, 1.0
	v_fmac_f32_e32 v42, v50, v42
	v_mul_f32_e32 v49, v19, v41
	v_div_scale_f32 v30, s[6:7], v3, v63, v3
	v_rcp_f32_e32 v48, v39
	v_fma_f32 v54, -v31, v44, 1.0
	v_fmac_f32_e32 v43, v51, v43
	v_mul_f32_e32 v50, v21, v42
	v_fma_f32 v59, -v18, v49, v19
	v_div_scale_f32 v32, s[8:9], v2, v62, v2
	v_fma_f32 v55, -v33, v45, 1.0
	v_fmac_f32_e32 v44, v54, v44
	v_mul_f32_e32 v51, v30, v43
	v_fma_f32 v66, -v20, v50, v21
	v_fmac_f32_e32 v49, v59, v41
	v_div_scale_f32 v34, s[10:11], v5, v61, v5
	v_fma_f32 v56, -v35, v46, 1.0
	v_fmac_f32_e32 v45, v55, v45
	v_mul_f32_e32 v54, v32, v44
	v_fma_f32 v67, -v29, v51, v30
	v_fmac_f32_e32 v50, v66, v42
	v_fma_f32 v18, -v18, v49, v19
	v_div_scale_f32 v36, s[12:13], v4, v60, v4
	v_fma_f32 v57, -v37, v47, 1.0
	v_fmac_f32_e32 v46, v56, v46
	v_mul_f32_e32 v55, v34, v45
	v_fma_f32 v68, -v31, v54, v32
	v_fmac_f32_e32 v51, v67, v43
	v_fma_f32 v19, -v20, v50, v21
	v_div_fmas_f32 v18, v18, v41, v49
	s_mov_b64 vcc, s[4:5]
	v_div_scale_f32 v38, s[14:15], v7, v53, v7
	v_fma_f32 v58, -v39, v48, 1.0
	v_fmac_f32_e32 v47, v57, v47
	v_mul_f32_e32 v56, v36, v46
	v_fma_f32 v69, -v33, v55, v34
	v_fmac_f32_e32 v54, v68, v44
	v_fma_f32 v20, -v29, v51, v30
	v_div_fixup_f32 v1, v18, v65, v1
	v_div_fmas_f32 v18, v19, v42, v50
	s_mov_b64 vcc, s[6:7]
	v_div_scale_f32 v40, s[16:17], v6, v52, v6
	v_fmac_f32_e32 v48, v58, v48
	v_mul_f32_e32 v57, v38, v47
	v_fma_f32 v70, -v35, v56, v36
	v_fmac_f32_e32 v55, v69, v45
	v_fma_f32 v21, -v31, v54, v32
	v_div_fixup_f32 v0, v18, v64, v0
	v_div_fmas_f32 v18, v20, v43, v51
	s_mov_b64 vcc, s[8:9]
	v_mul_f32_e32 v58, v40, v48
	v_fma_f32 v71, -v37, v57, v38
	v_fmac_f32_e32 v56, v70, v46
	v_fma_f32 v29, -v33, v55, v34
	v_cvt_pk_bf16_f32 v0, v0, v1
	v_div_fixup_f32 v1, v18, v63, v3
	v_div_fmas_f32 v3, v21, v44, v54
	s_mov_b64 vcc, s[10:11]
	v_fma_f32 v72, -v39, v58, v40
	v_fmac_f32_e32 v57, v71, v47
	v_fma_f32 v30, -v35, v56, v36
	v_div_fixup_f32 v2, v3, v62, v2
	v_div_fmas_f32 v3, v29, v45, v55
	s_mov_b64 vcc, s[12:13]
	v_fmac_f32_e32 v58, v72, v48
	v_fma_f32 v31, -v37, v57, v38
	v_cvt_pk_bf16_f32 v1, v2, v1
	v_div_fixup_f32 v2, v3, v61, v5
	v_div_fmas_f32 v3, v30, v46, v56
	s_mov_b64 vcc, s[14:15]
	v_fma_f32 v32, -v39, v58, v40
	v_div_fixup_f32 v3, v3, v60, v4
	v_div_fmas_f32 v4, v31, v47, v57
	s_mov_b64 vcc, s[16:17]
	v_cvt_pk_bf16_f32 v2, v3, v2
	v_div_fixup_f32 v3, v4, v53, v7
	v_div_fmas_f32 v4, v32, v48, v58
	v_div_fixup_f32 v4, v4, v52, v6
	v_cvt_pk_bf16_f32 v3, v4, v3
	global_store_dwordx4 v[22:23], v[0:3], off offset:1024
	v_mov_b32_e32 v22, v140
	v_mov_b32_e32 v23, v141
	s_andn2_b64 exec, exec, s[20:21]
	s_cbranch_execnz .LBB0_932
